# P13 up-proj GEMM epilogue: 8 per-row rsqrt loads hoisted and issued together, 7 serialising vmcnt(0) waits removed
# speedup vs baseline: 1.0066x; 1.0066x over previous
; __device__ __forceinline__ unsigned cvt_pk_bf16(float lo, float hi) { f32x2_c v = {lo, hi}; bf16x2_c b = __builtin_convertvector(v, bf16x2_c); return __builtin_bit_cast(unsigned, b); }
;     __device__ __forceinline__ void operator()(const f32x4 (&acc)[2][2][4][2], const Unit& u, int wr, int wc, int fr, int fq) const {
;         const int row0 = u.pm * BM + wr * 64 + fr, col0 = u.pn * BM + wc * 32 + 8 * fq;
; #pragma unroll
;         for (int ai = 0; ai < 2; ++ai)
; #pragma unroll
;             for (int m = 0; m < 4; ++m) { const size_t r = (size_t)(row0 + ai * HALF + m * 16); const float sc = rs[r];
; #pragma unroll
;                 for (int bj = 0; bj < 2; ++bj) { f32x4 v0 = acc[ai][bj][m][0] * sc, v1 = acc[ai][bj][m][1] * sc; const int c = col0 + bj * HALF;
; #pragma unroll
;                     for (int e = 0; e < 4; ++e) { const float a = fmaxf(v0[e], 0.f), b = fmaxf(v1[e], 0.f); v0[e] = a * a; v1[e] = b * b; }
;                     u32x4 w; w.x = cvt_pk_bf16(v0[0], v0[1]); w.y = cvt_pk_bf16(v0[2], v0[3]); w.z = cvt_pk_bf16(v1[0], v1[1]); w.w = cvt_pk_bf16(v1[2], v1[3]);
;                     *(u32x4*)(O + r * ldo + c) = w; } }
;     }
.LBB0_1688:
	v_lshl_add_u32 v150, s44, 8, v154
	v_ashrrev_i32_e32 v151, 31, v150
	v_lshl_add_u64 v[146:147], v[150:151], 2, s[12:13]
	global_load_dword v168, v[146:147], off
	global_load_dword v170, v[146:147], off offset:64
	global_load_dword v172, v[146:147], off offset:128
	global_load_dword v174, v[146:147], off offset:192
	global_load_dword v176, v[146:147], off offset:512
	global_load_dword v178, v[146:147], off offset:576
	global_load_dword v180, v[146:147], off offset:640
	global_load_dword v182, v[146:147], off offset:704
	v_lshl_or_b32 v148, s74, 8, v156
	v_ashrrev_i32_e32 v149, 31, v148
	v_lshlrev_b64 v[164:165], 14, v[150:151]
	v_or_b32_e32 v162, 16, v150
	v_lshlrev_b64 v[152:153], 1, v[148:149]
	v_lshl_add_u64 v[148:149], s[8:9], 0, v[164:165]
	v_ashrrev_i32_e32 v163, 31, v162
	v_lshl_add_u64 v[148:149], v[148:149], 0, v[152:153]
	s_waitcnt vmcnt(0)
	v_pk_mul_f32 v[128:129], v[128:129], v[168:169] op_sel_hi:[1,0]
	v_pk_mul_f32 v[126:127], v[126:127], v[168:169] op_sel_hi:[1,0]
	v_pk_mul_f32 v[124:125], v[124:125], v[168:169] op_sel_hi:[1,0]
	v_pk_mul_f32 v[122:123], v[122:123], v[168:169] op_sel_hi:[1,0]
	v_pk_mul_f32 v[120:121], v[120:121], v[168:169] op_sel_hi:[1,0]
	v_pk_mul_f32 v[118:119], v[118:119], v[168:169] op_sel_hi:[1,0]
	v_pk_mul_f32 v[116:117], v[116:117], v[168:169] op_sel_hi:[1,0]
	v_pk_mul_f32 v[114:115], v[114:115], v[168:169] op_sel_hi:[1,0]
	v_max_f32_e32 v126, 0, v126
	v_max_f32_e32 v122, 0, v122
	v_max_f32_e32 v127, 0, v127
	v_max_f32_e32 v123, 0, v123
	v_max_f32_e32 v128, 0, v128
	v_max_f32_e32 v124, 0, v124
	v_max_f32_e32 v129, 0, v129
	v_max_f32_e32 v125, 0, v125
	v_max_f32_e32 v118, 0, v118
	v_max_f32_e32 v114, 0, v114
	v_max_f32_e32 v119, 0, v119
	v_max_f32_e32 v115, 0, v115
	v_max_f32_e32 v120, 0, v120
	v_max_f32_e32 v116, 0, v116
	v_max_f32_e32 v121, 0, v121
	v_max_f32_e32 v117, 0, v117
	v_pk_mul_f32 v[126:127], v[126:127], v[126:127]
	v_pk_mul_f32 v[122:123], v[122:123], v[122:123]
	v_pk_mul_f32 v[128:129], v[128:129], v[128:129]
	v_pk_mul_f32 v[124:125], v[124:125], v[124:125]
	v_pk_mul_f32 v[118:119], v[118:119], v[118:119]
	v_pk_mul_f32 v[160:161], v[114:115], v[114:115]
	v_pk_mul_f32 v[120:121], v[120:121], v[120:121]
	v_pk_mul_f32 v[166:167], v[116:117], v[116:117]
	v_cvt_pk_bf16_f32 v114, v126, v127
	v_cvt_pk_bf16_f32 v115, v128, v129
	v_cvt_pk_bf16_f32 v116, v122, v123
	v_cvt_pk_bf16_f32 v117, v124, v125
	v_cvt_pk_bf16_f32 v118, v118, v119
	v_cvt_pk_bf16_f32 v119, v120, v121
	v_cvt_pk_bf16_f32 v120, v160, v161
	v_cvt_pk_bf16_f32 v121, v166, v167
	global_store_dwordx4 v[148:149], v[114:117], off
	global_store_dwordx4 v[148:149], v[118:121], off offset:256
	s_nop 0
	v_or_b32_e32 v116, 32, v150
	v_lshlrev_b64 v[118:119], 14, v[162:163]
	v_lshl_add_u64 v[118:119], s[8:9], 0, v[118:119]
	v_ashrrev_i32_e32 v117, 31, v116
	v_lshl_add_u64 v[118:119], v[118:119], 0, v[152:153]
	v_pk_mul_f32 v[112:113], v[112:113], v[170:171] op_sel_hi:[1,0]
	v_pk_mul_f32 v[110:111], v[110:111], v[170:171] op_sel_hi:[1,0]
	v_pk_mul_f32 v[108:109], v[108:109], v[170:171] op_sel_hi:[1,0]
	v_pk_mul_f32 v[106:107], v[106:107], v[170:171] op_sel_hi:[1,0]
	v_pk_mul_f32 v[104:105], v[104:105], v[170:171] op_sel_hi:[1,0]
	v_pk_mul_f32 v[102:103], v[102:103], v[170:171] op_sel_hi:[1,0]
	v_pk_mul_f32 v[100:101], v[100:101], v[170:171] op_sel_hi:[1,0]
	v_pk_mul_f32 v[98:99], v[98:99], v[170:171] op_sel_hi:[1,0]
	v_max_f32_e32 v110, 0, v110
	v_max_f32_e32 v106, 0, v106
	v_max_f32_e32 v111, 0, v111
	v_max_f32_e32 v107, 0, v107
	v_max_f32_e32 v112, 0, v112
	v_max_f32_e32 v108, 0, v108
	v_max_f32_e32 v113, 0, v113
	v_max_f32_e32 v109, 0, v109
	v_max_f32_e32 v102, 0, v102
	v_max_f32_e32 v98, 0, v98
	v_max_f32_e32 v103, 0, v103
	v_max_f32_e32 v99, 0, v99
	v_max_f32_e32 v104, 0, v104
	v_max_f32_e32 v100, 0, v100
	v_max_f32_e32 v105, 0, v105
	v_max_f32_e32 v101, 0, v101
	v_pk_mul_f32 v[110:111], v[110:111], v[110:111]
	v_pk_mul_f32 v[106:107], v[106:107], v[106:107]
	v_pk_mul_f32 v[112:113], v[112:113], v[112:113]
	v_pk_mul_f32 v[108:109], v[108:109], v[108:109]
	v_pk_mul_f32 v[102:103], v[102:103], v[102:103]
	v_pk_mul_f32 v[114:115], v[98:99], v[98:99]
	v_pk_mul_f32 v[104:105], v[104:105], v[104:105]
	v_pk_mul_f32 v[122:123], v[100:101], v[100:101]
	v_cvt_pk_bf16_f32 v98, v110, v111
	v_cvt_pk_bf16_f32 v99, v112, v113
	v_cvt_pk_bf16_f32 v100, v106, v107
	v_cvt_pk_bf16_f32 v101, v108, v109
	v_cvt_pk_bf16_f32 v102, v102, v103
	v_cvt_pk_bf16_f32 v103, v104, v105
	v_cvt_pk_bf16_f32 v104, v114, v115
	v_cvt_pk_bf16_f32 v105, v122, v123
	global_store_dwordx4 v[118:119], v[98:101], off
	global_store_dwordx4 v[118:119], v[102:105], off offset:256
	s_nop 0
	v_or_b32_e32 v100, 48, v150
	v_lshlrev_b64 v[102:103], 14, v[116:117]
	v_lshl_add_u64 v[102:103], s[8:9], 0, v[102:103]
	v_ashrrev_i32_e32 v101, 31, v100
	v_lshl_add_u64 v[102:103], v[102:103], 0, v[152:153]
	v_pk_mul_f32 v[96:97], v[96:97], v[172:173] op_sel_hi:[1,0]
	v_pk_mul_f32 v[94:95], v[94:95], v[172:173] op_sel_hi:[1,0]
	v_pk_mul_f32 v[92:93], v[92:93], v[172:173] op_sel_hi:[1,0]
	v_pk_mul_f32 v[90:91], v[90:91], v[172:173] op_sel_hi:[1,0]
	v_pk_mul_f32 v[88:89], v[88:89], v[172:173] op_sel_hi:[1,0]
	v_pk_mul_f32 v[86:87], v[86:87], v[172:173] op_sel_hi:[1,0]
	v_pk_mul_f32 v[84:85], v[84:85], v[172:173] op_sel_hi:[1,0]
	v_pk_mul_f32 v[82:83], v[82:83], v[172:173] op_sel_hi:[1,0]
	v_max_f32_e32 v94, 0, v94
	v_max_f32_e32 v90, 0, v90
	v_max_f32_e32 v95, 0, v95
	v_max_f32_e32 v91, 0, v91
	v_max_f32_e32 v96, 0, v96
	v_max_f32_e32 v92, 0, v92
	v_max_f32_e32 v97, 0, v97
	v_max_f32_e32 v93, 0, v93
	v_max_f32_e32 v86, 0, v86
	v_max_f32_e32 v82, 0, v82
	v_max_f32_e32 v87, 0, v87
; __device__ __forceinline__ unsigned cvt_pk_bf16(float lo, float hi) { f32x2_c v = {lo, hi}; bf16x2_c b = __builtin_convertvector(v, bf16x2_c); return __builtin_bit_cast(unsigned, b); }
;     __device__ __forceinline__ void operator()(const f32x4 (&acc)[2][2][4][2], const Unit& u, int wr, int wc, int fr, int fq) const {
;         const int row0 = u.pm * BM + wr * 64 + fr, col0 = u.pn * BM + wc * 32 + 8 * fq;
; #pragma unroll
;         for (int ai = 0; ai < 2; ++ai)
; #pragma unroll
;             for (int m = 0; m < 4; ++m) { const size_t r = (size_t)(row0 + ai * HALF + m * 16); const float sc = rs[r];
; #pragma unroll
;                 for (int bj = 0; bj < 2; ++bj) { f32x4 v0 = acc[ai][bj][m][0] * sc, v1 = acc[ai][bj][m][1] * sc; const int c = col0 + bj * HALF;
; #pragma unroll
;                     for (int e = 0; e < 4; ++e) { const float a = fmaxf(v0[e], 0.f), b = fmaxf(v1[e], 0.f); v0[e] = a * a; v1[e] = b * b; }
;                     u32x4 w; w.x = cvt_pk_bf16(v0[0], v0[1]); w.y = cvt_pk_bf16(v0[2], v0[3]); w.z = cvt_pk_bf16(v1[0], v1[1]); w.w = cvt_pk_bf16(v1[2], v1[3]);
;                     *(u32x4*)(O + r * ldo + c) = w; } }
;     }
	v_max_f32_e32 v83, 0, v83
	v_max_f32_e32 v88, 0, v88
	v_max_f32_e32 v84, 0, v84
	v_max_f32_e32 v89, 0, v89
	v_max_f32_e32 v85, 0, v85
	v_pk_mul_f32 v[94:95], v[94:95], v[94:95]
	v_pk_mul_f32 v[90:91], v[90:91], v[90:91]
	v_pk_mul_f32 v[96:97], v[96:97], v[96:97]
	v_pk_mul_f32 v[92:93], v[92:93], v[92:93]
	v_pk_mul_f32 v[86:87], v[86:87], v[86:87]
	v_pk_mul_f32 v[98:99], v[82:83], v[82:83]
	v_pk_mul_f32 v[88:89], v[88:89], v[88:89]
	v_pk_mul_f32 v[106:107], v[84:85], v[84:85]
	v_cvt_pk_bf16_f32 v82, v94, v95
	v_cvt_pk_bf16_f32 v83, v96, v97
	v_cvt_pk_bf16_f32 v84, v90, v91
	v_cvt_pk_bf16_f32 v85, v92, v93
	v_cvt_pk_bf16_f32 v86, v86, v87
	v_cvt_pk_bf16_f32 v87, v88, v89
	v_cvt_pk_bf16_f32 v88, v98, v99
	v_cvt_pk_bf16_f32 v89, v106, v107
	global_store_dwordx4 v[102:103], v[82:85], off
	global_store_dwordx4 v[102:103], v[86:89], off offset:256
	s_nop 0
	v_lshlrev_b64 v[84:85], 14, v[100:101]
	v_lshl_add_u64 v[84:85], s[8:9], 0, v[84:85]
	v_lshl_add_u64 v[84:85], v[84:85], 0, v[152:153]
	v_pk_mul_f32 v[80:81], v[80:81], v[174:175] op_sel_hi:[1,0]
	v_pk_mul_f32 v[78:79], v[78:79], v[174:175] op_sel_hi:[1,0]
	v_pk_mul_f32 v[76:77], v[76:77], v[174:175] op_sel_hi:[1,0]
	v_pk_mul_f32 v[74:75], v[74:75], v[174:175] op_sel_hi:[1,0]
	v_pk_mul_f32 v[72:73], v[72:73], v[174:175] op_sel_hi:[1,0]
	v_pk_mul_f32 v[70:71], v[70:71], v[174:175] op_sel_hi:[1,0]
	v_pk_mul_f32 v[68:69], v[68:69], v[174:175] op_sel_hi:[1,0]
	v_pk_mul_f32 v[66:67], v[66:67], v[174:175] op_sel_hi:[1,0]
	v_max_f32_e32 v78, 0, v78
	v_max_f32_e32 v74, 0, v74
	v_max_f32_e32 v79, 0, v79
	v_max_f32_e32 v75, 0, v75
	v_max_f32_e32 v80, 0, v80
	v_max_f32_e32 v76, 0, v76
	v_max_f32_e32 v81, 0, v81
	v_max_f32_e32 v77, 0, v77
	v_max_f32_e32 v70, 0, v70
	v_max_f32_e32 v66, 0, v66
	v_max_f32_e32 v71, 0, v71
	v_max_f32_e32 v67, 0, v67
	v_max_f32_e32 v72, 0, v72
	v_max_f32_e32 v68, 0, v68
	v_max_f32_e32 v73, 0, v73
	v_max_f32_e32 v69, 0, v69
	v_pk_mul_f32 v[78:79], v[78:79], v[78:79]
	v_pk_mul_f32 v[74:75], v[74:75], v[74:75]
	v_pk_mul_f32 v[80:81], v[80:81], v[80:81]
	v_pk_mul_f32 v[76:77], v[76:77], v[76:77]
	v_pk_mul_f32 v[70:71], v[70:71], v[70:71]
	v_pk_mul_f32 v[82:83], v[66:67], v[66:67]
	v_pk_mul_f32 v[72:73], v[72:73], v[72:73]
	v_pk_mul_f32 v[86:87], v[68:69], v[68:69]
	v_cvt_pk_bf16_f32 v66, v78, v79
	v_cvt_pk_bf16_f32 v67, v80, v81
	v_cvt_pk_bf16_f32 v68, v74, v75
	v_cvt_pk_bf16_f32 v69, v76, v77
	v_cvt_pk_bf16_f32 v70, v70, v71
	v_cvt_pk_bf16_f32 v71, v72, v73
	v_cvt_pk_bf16_f32 v72, v82, v83
	v_cvt_pk_bf16_f32 v73, v86, v87
	global_store_dwordx4 v[84:85], v[66:69], off
	global_store_dwordx4 v[84:85], v[70:73], off offset:256
	s_nop 0
	v_lshl_add_u64 v[68:69], v[148:149], 0, s[20:21]
	v_add_co_u32_e32 v70, vcc, s70, v148
	v_pk_mul_f32 v[64:65], v[64:65], v[176:177] op_sel_hi:[1,0]
	v_pk_mul_f32 v[62:63], v[62:63], v[176:177] op_sel_hi:[1,0]
	v_pk_mul_f32 v[60:61], v[60:61], v[176:177] op_sel_hi:[1,0]
	v_pk_mul_f32 v[58:59], v[58:59], v[176:177] op_sel_hi:[1,0]
	v_pk_mul_f32 v[56:57], v[56:57], v[176:177] op_sel_hi:[1,0]
	v_pk_mul_f32 v[54:55], v[54:55], v[176:177] op_sel_hi:[1,0]
	v_pk_mul_f32 v[52:53], v[52:53], v[176:177] op_sel_hi:[1,0]
	v_pk_mul_f32 v[50:51], v[50:51], v[176:177] op_sel_hi:[1,0]
	v_max_f32_e32 v62, 0, v62
	v_max_f32_e32 v58, 0, v58
	v_max_f32_e32 v63, 0, v63
	v_max_f32_e32 v59, 0, v59
	v_max_f32_e32 v64, 0, v64
	v_max_f32_e32 v60, 0, v60
	v_max_f32_e32 v65, 0, v65
	v_max_f32_e32 v61, 0, v61
	v_max_f32_e32 v54, 0, v54
	v_max_f32_e32 v50, 0, v50
	v_max_f32_e32 v55, 0, v55
	v_max_f32_e32 v51, 0, v51
	v_max_f32_e32 v56, 0, v56
	v_max_f32_e32 v52, 0, v52
	v_max_f32_e32 v57, 0, v57
	v_max_f32_e32 v53, 0, v53
	v_pk_mul_f32 v[62:63], v[62:63], v[62:63]
	v_pk_mul_f32 v[58:59], v[58:59], v[58:59]
	v_pk_mul_f32 v[64:65], v[64:65], v[64:65]
	v_pk_mul_f32 v[60:61], v[60:61], v[60:61]
	v_addc_co_u32_e32 v71, vcc, 0, v149, vcc
	v_pk_mul_f32 v[54:55], v[54:55], v[54:55]
	v_pk_mul_f32 v[66:67], v[50:51], v[50:51]
	v_pk_mul_f32 v[56:57], v[56:57], v[56:57]
	v_pk_mul_f32 v[72:73], v[52:53], v[52:53]
	v_cvt_pk_bf16_f32 v50, v62, v63
	v_cvt_pk_bf16_f32 v51, v64, v65
	v_cvt_pk_bf16_f32 v52, v58, v59
	v_cvt_pk_bf16_f32 v53, v60, v61
	v_cvt_pk_bf16_f32 v54, v54, v55
	v_cvt_pk_bf16_f32 v55, v56, v57
	v_cvt_pk_bf16_f32 v56, v66, v67
	v_cvt_pk_bf16_f32 v57, v72, v73
	global_store_dwordx4 v[70:71], v[50:53], off
	global_store_dwordx4 v[68:69], v[54:57], off offset:256
	s_nop 0
	v_lshl_add_u64 v[52:53], v[148:149], 0, s[22:23]
	v_add_co_u32_e32 v54, vcc, s71, v148
	v_pk_mul_f32 v[48:49], v[48:49], v[178:179] op_sel_hi:[1,0]
	v_pk_mul_f32 v[46:47], v[46:47], v[178:179] op_sel_hi:[1,0]
	v_pk_mul_f32 v[44:45], v[44:45], v[178:179] op_sel_hi:[1,0]
	v_pk_mul_f32 v[42:43], v[42:43], v[178:179] op_sel_hi:[1,0]
	v_pk_mul_f32 v[40:41], v[40:41], v[178:179] op_sel_hi:[1,0]
	v_pk_mul_f32 v[38:39], v[38:39], v[178:179] op_sel_hi:[1,0]
	v_pk_mul_f32 v[36:37], v[36:37], v[178:179] op_sel_hi:[1,0]
; __device__ __forceinline__ unsigned cvt_pk_bf16(float lo, float hi) { f32x2_c v = {lo, hi}; bf16x2_c b = __builtin_convertvector(v, bf16x2_c); return __builtin_bit_cast(unsigned, b); }
;     __device__ __forceinline__ void operator()(const f32x4 (&acc)[2][2][4][2], const Unit& u, int wr, int wc, int fr, int fq) const {
;         const int row0 = u.pm * BM + wr * 64 + fr, col0 = u.pn * BM + wc * 32 + 8 * fq;
; #pragma unroll
;         for (int ai = 0; ai < 2; ++ai)
; #pragma unroll
;             for (int m = 0; m < 4; ++m) { const size_t r = (size_t)(row0 + ai * HALF + m * 16); const float sc = rs[r];
; #pragma unroll
;                 for (int bj = 0; bj < 2; ++bj) { f32x4 v0 = acc[ai][bj][m][0] * sc, v1 = acc[ai][bj][m][1] * sc; const int c = col0 + bj * HALF;
; #pragma unroll
;                     for (int e = 0; e < 4; ++e) { const float a = fmaxf(v0[e], 0.f), b = fmaxf(v1[e], 0.f); v0[e] = a * a; v1[e] = b * b; }
;                     u32x4 w; w.x = cvt_pk_bf16(v0[0], v0[1]); w.y = cvt_pk_bf16(v0[2], v0[3]); w.z = cvt_pk_bf16(v1[0], v1[1]); w.w = cvt_pk_bf16(v1[2], v1[3]);
;                     *(u32x4*)(O + r * ldo + c) = w; } }
;     }
	v_pk_mul_f32 v[34:35], v[34:35], v[178:179] op_sel_hi:[1,0]
	v_max_f32_e32 v46, 0, v46
	v_max_f32_e32 v42, 0, v42
	v_max_f32_e32 v47, 0, v47
	v_max_f32_e32 v43, 0, v43
	v_max_f32_e32 v48, 0, v48
	v_max_f32_e32 v44, 0, v44
	v_max_f32_e32 v49, 0, v49
	v_max_f32_e32 v45, 0, v45
	v_max_f32_e32 v38, 0, v38
	v_max_f32_e32 v34, 0, v34
	v_max_f32_e32 v39, 0, v39
	v_max_f32_e32 v35, 0, v35
	v_max_f32_e32 v40, 0, v40
	v_max_f32_e32 v36, 0, v36
	v_max_f32_e32 v41, 0, v41
	v_max_f32_e32 v37, 0, v37
	v_pk_mul_f32 v[46:47], v[46:47], v[46:47]
	v_pk_mul_f32 v[42:43], v[42:43], v[42:43]
	v_pk_mul_f32 v[48:49], v[48:49], v[48:49]
	v_pk_mul_f32 v[44:45], v[44:45], v[44:45]
	v_addc_co_u32_e32 v55, vcc, 0, v149, vcc
	v_pk_mul_f32 v[38:39], v[38:39], v[38:39]
	v_pk_mul_f32 v[50:51], v[34:35], v[34:35]
	v_pk_mul_f32 v[40:41], v[40:41], v[40:41]
	v_pk_mul_f32 v[56:57], v[36:37], v[36:37]
	v_cvt_pk_bf16_f32 v34, v46, v47
	v_cvt_pk_bf16_f32 v35, v48, v49
	v_cvt_pk_bf16_f32 v36, v42, v43
	v_cvt_pk_bf16_f32 v37, v44, v45
	v_cvt_pk_bf16_f32 v38, v38, v39
	v_cvt_pk_bf16_f32 v39, v40, v41
	v_cvt_pk_bf16_f32 v40, v50, v51
	v_cvt_pk_bf16_f32 v41, v56, v57
	global_store_dwordx4 v[54:55], v[34:37], off
	global_store_dwordx4 v[52:53], v[38:41], off offset:256
	s_nop 0
	v_lshl_add_u64 v[36:37], v[148:149], 0, s[24:25]
	v_add_co_u32_e32 v38, vcc, s72, v148
	v_pk_mul_f32 v[32:33], v[32:33], v[180:181] op_sel_hi:[1,0]
	v_pk_mul_f32 v[30:31], v[30:31], v[180:181] op_sel_hi:[1,0]
	v_pk_mul_f32 v[28:29], v[28:29], v[180:181] op_sel_hi:[1,0]
	v_pk_mul_f32 v[26:27], v[26:27], v[180:181] op_sel_hi:[1,0]
	v_pk_mul_f32 v[24:25], v[24:25], v[180:181] op_sel_hi:[1,0]
	v_pk_mul_f32 v[22:23], v[22:23], v[180:181] op_sel_hi:[1,0]
	v_pk_mul_f32 v[20:21], v[20:21], v[180:181] op_sel_hi:[1,0]
	v_pk_mul_f32 v[18:19], v[18:19], v[180:181] op_sel_hi:[1,0]
	v_max_f32_e32 v30, 0, v30
	v_max_f32_e32 v26, 0, v26
	v_max_f32_e32 v31, 0, v31
	v_max_f32_e32 v27, 0, v27
	v_max_f32_e32 v32, 0, v32
	v_max_f32_e32 v28, 0, v28
	v_max_f32_e32 v33, 0, v33
	v_max_f32_e32 v29, 0, v29
	v_max_f32_e32 v22, 0, v22
	v_max_f32_e32 v18, 0, v18
	v_max_f32_e32 v23, 0, v23
	v_max_f32_e32 v19, 0, v19
	v_max_f32_e32 v24, 0, v24
	v_max_f32_e32 v20, 0, v20
	v_max_f32_e32 v25, 0, v25
	v_max_f32_e32 v21, 0, v21
	v_pk_mul_f32 v[30:31], v[30:31], v[30:31]
	v_pk_mul_f32 v[26:27], v[26:27], v[26:27]
	v_pk_mul_f32 v[32:33], v[32:33], v[32:33]
	v_pk_mul_f32 v[28:29], v[28:29], v[28:29]
	v_addc_co_u32_e32 v39, vcc, 0, v149, vcc
	v_pk_mul_f32 v[22:23], v[22:23], v[22:23]
	v_pk_mul_f32 v[34:35], v[18:19], v[18:19]
	v_pk_mul_f32 v[24:25], v[24:25], v[24:25]
	v_pk_mul_f32 v[40:41], v[20:21], v[20:21]
	v_cvt_pk_bf16_f32 v18, v30, v31
	v_cvt_pk_bf16_f32 v19, v32, v33
	v_cvt_pk_bf16_f32 v20, v26, v27
	v_cvt_pk_bf16_f32 v21, v28, v29
	v_cvt_pk_bf16_f32 v22, v22, v23
	v_cvt_pk_bf16_f32 v23, v24, v25
	v_cvt_pk_bf16_f32 v24, v34, v35
	v_cvt_pk_bf16_f32 v25, v40, v41
	global_store_dwordx4 v[38:39], v[18:21], off
	global_store_dwordx4 v[36:37], v[22:25], off offset:256
	s_nop 0
	s_andn2_b64 vcc, exec, s[0:1]
	v_add_co_u32_e64 v22, s[0:1], s73, v148
	v_lshl_add_u64 v[20:21], v[148:149], 0, s[26:27]
	s_nop 0
	v_addc_co_u32_e64 v23, s[0:1], 0, v149, s[0:1]
	s_mov_b64 s[0:1], -1
	v_pk_mul_f32 v[16:17], v[16:17], v[182:183] op_sel_hi:[1,0]
	v_pk_mul_f32 v[14:15], v[14:15], v[182:183] op_sel_hi:[1,0]
	v_pk_mul_f32 v[12:13], v[12:13], v[182:183] op_sel_hi:[1,0]
	v_pk_mul_f32 v[10:11], v[10:11], v[182:183] op_sel_hi:[1,0]
	v_pk_mul_f32 v[8:9], v[8:9], v[182:183] op_sel_hi:[1,0]
	v_pk_mul_f32 v[6:7], v[6:7], v[182:183] op_sel_hi:[1,0]
	v_pk_mul_f32 v[4:5], v[4:5], v[182:183] op_sel_hi:[1,0]
	v_pk_mul_f32 v[2:3], v[2:3], v[182:183] op_sel_hi:[1,0]
	v_max_f32_e32 v14, 0, v14
	v_max_f32_e32 v10, 0, v10
	v_max_f32_e32 v15, 0, v15
	v_max_f32_e32 v11, 0, v11
	v_max_f32_e32 v16, 0, v16
	v_max_f32_e32 v12, 0, v12
	v_max_f32_e32 v17, 0, v17
	v_max_f32_e32 v13, 0, v13
	v_max_f32_e32 v6, 0, v6
	v_max_f32_e32 v2, 0, v2
	v_max_f32_e32 v7, 0, v7
	v_max_f32_e32 v3, 0, v3
	v_max_f32_e32 v8, 0, v8
	v_max_f32_e32 v4, 0, v4
	v_max_f32_e32 v9, 0, v9
	v_max_f32_e32 v5, 0, v5
	v_pk_mul_f32 v[14:15], v[14:15], v[14:15]
	v_pk_mul_f32 v[10:11], v[10:11], v[10:11]
	v_pk_mul_f32 v[16:17], v[16:17], v[16:17]
	v_pk_mul_f32 v[12:13], v[12:13], v[12:13]
	v_pk_mul_f32 v[6:7], v[6:7], v[6:7]
	v_pk_mul_f32 v[18:19], v[2:3], v[2:3]
	v_pk_mul_f32 v[8:9], v[8:9], v[8:9]
	v_pk_mul_f32 v[24:25], v[4:5], v[4:5]
	v_cvt_pk_bf16_f32 v2, v14, v15
	v_cvt_pk_bf16_f32 v3, v16, v17
	v_cvt_pk_bf16_f32 v4, v10, v11
	v_cvt_pk_bf16_f32 v5, v12, v13
	v_cvt_pk_bf16_f32 v6, v6, v7
	v_cvt_pk_bf16_f32 v7, v8, v9
	v_cvt_pk_bf16_f32 v8, v18, v19
	v_cvt_pk_bf16_f32 v9, v24, v25
	global_store_dwordx4 v[22:23], v[2:5], off
	global_store_dwordx4 v[20:21], v[6:9], off offset:256
	s_cbranch_vccnz .LBB0_1677
	s_andn2_b64 vcc, exec, s[6:7]
	s_cbranch_vccnz .LBB0_1676
	s_barrier
	s_branch .LBB0_1676
